# in-projection q/k epilogue: RMSNorm gain vector staged once per tile in a wave-private LDS slot and read with ds_read_b128, so the 32 per-tile gain reads no longer queue behind result stores with vmcn
# speedup vs baseline: 1.0103x; 1.0103x over previous
.LBB0_957:
	v_mul_f32_e32 v133, v115, v115
	v_fmac_f32_e32 v133, v114, v114
	v_fmac_f32_e32 v133, v116, v116
	v_fmac_f32_e32 v133, v117, v117
	v_fmac_f32_e32 v133, v118, v118
	v_fmac_f32_e32 v133, v119, v119
	v_fmac_f32_e32 v133, v120, v120
	v_fmac_f32_e32 v133, v121, v121
	v_fmac_f32_e32 v133, v122, v122
	v_fmac_f32_e32 v133, v123, v123
	v_fmac_f32_e32 v133, v124, v124
	v_fmac_f32_e32 v133, v125, v125
	v_fmac_f32_e32 v133, v126, v126
	v_fmac_f32_e32 v133, v127, v127
	v_fmac_f32_e32 v133, v128, v128
	v_fmac_f32_e32 v133, v129, v129
	v_fmac_f32_e32 v133, v82, v82
	v_fmac_f32_e32 v133, v83, v83
	v_fmac_f32_e32 v133, v84, v84
	v_fmac_f32_e32 v133, v85, v85
	v_fmac_f32_e32 v133, v86, v86
	v_fmac_f32_e32 v133, v87, v87
	v_pk_mul_f32 v[146:147], v[88:89], v[88:89]
	v_pk_mul_f32 v[144:145], v[90:91], v[90:91]
	v_add_f32_e32 v133, v146, v133
	v_add_f32_e32 v133, v147, v133
	v_add_f32_e32 v133, v144, v133
	v_and_b32_e32 v131, 64, v195
	v_pk_mul_f32 v[142:143], v[92:93], v[92:93]
	v_add_f32_e32 v133, v145, v133
	v_xor_b32_e32 v130, 32, v195
	v_add_u32_e32 v131, 64, v131
	v_add_f32_e32 v133, v142, v133
	v_cmp_lt_i32_e32 vcc, v130, v131
	v_pk_mul_f32 v[140:141], v[94:95], v[94:95]
	v_add_f32_e32 v133, v143, v133
	v_cndmask_b32_e32 v130, v195, v130, vcc
	v_add_f32_e32 v133, v140, v133
	v_lshlrev_b32_e32 v135, 2, v130
	v_pk_mul_f32 v[130:131], v[96:97], v[96:97]
	v_add_f32_e32 v133, v141, v133
	v_add_f32_e32 v130, v130, v133
	v_add_f32_e32 v130, v131, v130
	ds_bpermute_b32 v131, v135, v130
	v_lshlrev_b32_e32 v138, 4, v132
	v_lshlrev_b32_e32 v156, 2, v132
	s_cmp_eq_u32 s37, 2
	s_cselect_b64 s[0:1], -1, 0
	s_waitcnt lgkmcnt(0)
	v_add_f32_e32 v130, v130, v131
	v_fmamk_f32 v137, v130, 0x3c800000, v188
	v_and_b32_e32 v249, 63, v184
	v_lshlrev_b32_e32 v250, 2, v249
	global_load_dword v251, v250, s[28:29]
	v_lshrrev_b32_e32 v252, 6, v184
	v_lshlrev_b32_e32 v252, 8, v252
	v_add_u32_e32 v252, 0x10000, v252
	v_add_u32_e32 v253, v252, v250
	v_add_u32_e32 v252, v252, v138
	s_waitcnt vmcnt(0)
	ds_write_b32 v253, v251
	s_waitcnt lgkmcnt(0)
	ds_read_b128 v[130:133], v252
	s_cmp_lt_i32 s36, 64
	s_cselect_b64 s[36:37], -1, 0
	s_and_b64 s[0:1], s[36:37], s[0:1]
	s_mov_b32 s4, 0x800000
	v_or_b32_e32 v140, v136, v156
	s_mov_b64 s[38:39], -1
	v_cmp_gt_f32_e64 s[36:37], s4, v137
	s_and_b64 vcc, exec, s[0:1]
	v_ashrrev_i32_e32 v141, 31, v140
	s_cbranch_vccnz .LBB0_959
	s_mov_b64 s[38:39], 0
.LBB0_959:
	v_mul_f32_e32 v142, 0x4b800000, v137
	v_cndmask_b32_e64 v137, v137, v142, s[36:37]
	v_rsq_f32_e32 v137, v137
	v_or_b32_e32 v170, v134, v139
	v_ashrrev_i32_e32 v171, 31, v170
	v_readlane_b32 s4, v246, 44
	v_mul_f32_e32 v139, 0x45800000, v137
	v_cndmask_b32_e64 v180, v137, v139, s[36:37]
	v_pk_mul_f32 v[144:145], v[114:115], v[180:181] op_sel_hi:[1,0]
	v_lshlrev_b64 v[142:143], 11, v[170:171]
	s_waitcnt vmcnt(0) lgkmcnt(0)
	v_pk_mul_f32 v[130:131], v[130:131], v[144:145]
	v_pk_mul_f32 v[144:145], v[116:117], v[180:181] op_sel_hi:[1,0]
	v_readlane_b32 s5, v246, 45
	v_pk_mul_f32 v[132:133], v[132:133], v[144:145]
	s_andn2_b64 vcc, exec, s[38:39]
	v_lshl_add_u64 v[172:173], s[4:5], 0, v[142:143]
	v_ashrrev_i32_e32 v203, 31, v1
	s_cbranch_vccnz .LBB0_961
	s_ashr_i32 s23, s24, 31
	v_mov_b32_e32 v137, s23
	v_subrev_co_u32_e32 v142, vcc, s24, v1
	v_mov_b32_e32 v157, v0
	s_nop 0
	v_subb_co_u32_e32 v143, vcc, v203, v137, vcc
	v_lshl_add_u64 v[142:143], v[142:143], 0, v[156:157]
	v_lshl_add_u64 v[142:143], v[142:143], 2, v[172:173]
	global_store_dwordx4 v[142:143], v[130:133], off offset:-2048
.LBB0_961:
	s_xor_b64 s[38:39], s[0:1], -1
	v_mov_b32_e32 v139, v0
	v_lshl_add_u64 v[138:139], s[28:29], 0, v[138:139]
	s_add_u32 s28, s68, s34
	s_addc_u32 s29, s69, s35
	v_lshlrev_b64 v[142:143], 10, v[170:171]
	v_lshl_add_u64 v[174:175], s[28:29], 0, v[142:143]
	v_pk_mul_f32 v[130:131], s[22:23], v[130:131] op_sel_hi:[0,1]
	v_pk_mul_f32 v[132:133], s[22:23], v[132:133] op_sel_hi:[0,1]
	v_cvt_pk_bf16_f32 v130, v130, v131
	v_cvt_pk_bf16_f32 v131, v132, v133
	v_lshl_add_u64 v[132:133], v[140:141], 1, v[174:175]
	global_store_dwordx2 v[132:133], v[130:131], off
	ds_read_b128 v[130:133], v252 offset:32
	v_or_b32_e32 v158, 8, v156
	v_or_b32_e32 v142, v136, v158
	v_cndmask_b32_e64 v137, 0, 1, s[38:39]
	s_mov_b64 s[34:35], -1
	v_cmp_ne_u32_e64 s[36:37], 1, v137
	s_andn2_b64 vcc, exec, s[38:39]
	v_ashrrev_i32_e32 v143, 31, v142
	s_cbranch_vccnz .LBB0_963
	s_mov_b64 s[34:35], 0
.LBB0_963:
	v_mov_b32_e32 v181, v180
	v_pk_mul_f32 v[144:145], v[118:119], v[180:181]
	s_andn2_b64 vcc, exec, s[34:35]
	s_waitcnt vmcnt(8) lgkmcnt(0)
	v_pk_mul_f32 v[130:131], v[144:145], v[130:131]
	v_pk_mul_f32 v[144:145], v[120:121], v[180:181]
	s_nop 0
	v_pk_mul_f32 v[132:133], v[144:145], v[132:133]
	s_cbranch_vccnz .LBB0_965
	s_ashr_i32 s23, s24, 31
	v_mov_b32_e32 v137, s23
	v_subrev_co_u32_e32 v144, vcc, s24, v1
	v_mov_b32_e32 v159, v0
	s_nop 0
	v_subb_co_u32_e32 v145, vcc, v203, v137, vcc
	v_lshl_add_u64 v[144:145], v[144:145], 0, v[158:159]
	v_lshl_add_u64 v[144:145], v[144:145], 2, v[172:173]
	global_store_dwordx4 v[144:145], v[130:133], off offset:-2048
.LBB0_965:
	s_mov_b32 s23, s22
	s_nop 0
	v_pk_mul_f32 v[130:131], s[22:23], v[130:131]
	v_pk_mul_f32 v[132:133], s[22:23], v[132:133]
	v_cvt_pk_bf16_f32 v130, v130, v131
	v_cvt_pk_bf16_f32 v131, v132, v133
	v_lshl_add_u64 v[132:133], v[142:143], 1, v[174:175]
	global_store_dwordx2 v[132:133], v[130:131], off
	ds_read_b128 v[130:133], v252 offset:64
	v_or_b32_e32 v160, 16, v156
	v_or_b32_e32 v144, v136, v160
	s_mov_b64 s[34:35], -1
	s_and_b64 vcc, exec, s[36:37]
	v_ashrrev_i32_e32 v145, 31, v144
	s_cbranch_vccnz .LBB0_967
	s_mov_b64 s[34:35], 0
.LBB0_967:
	v_pk_mul_f32 v[146:147], v[122:123], v[180:181]
	s_andn2_b64 vcc, exec, s[34:35]
	s_waitcnt vmcnt(8) lgkmcnt(0)
	v_pk_mul_f32 v[130:131], v[146:147], v[130:131]
	v_pk_mul_f32 v[146:147], v[124:125], v[180:181]
	s_nop 0
	v_pk_mul_f32 v[132:133], v[146:147], v[132:133]
	s_cbranch_vccnz .LBB0_969
	s_ashr_i32 s34, s24, 31
	v_mov_b32_e32 v137, s34
	v_subrev_co_u32_e32 v146, vcc, s24, v1
	v_mov_b32_e32 v161, v0
	s_nop 0
	v_subb_co_u32_e32 v147, vcc, v203, v137, vcc
	v_lshl_add_u64 v[146:147], v[146:147], 0, v[160:161]
	v_lshl_add_u64 v[146:147], v[146:147], 2, v[172:173]
	global_store_dwordx4 v[146:147], v[130:133], off offset:-2048
.LBB0_969:
	s_nop 1
	v_pk_mul_f32 v[130:131], s[22:23], v[130:131]
	v_pk_mul_f32 v[132:133], s[22:23], v[132:133]
	v_cvt_pk_bf16_f32 v130, v130, v131
	v_cvt_pk_bf16_f32 v131, v132, v133
	v_lshl_add_u64 v[132:133], v[144:145], 1, v[174:175]
	global_store_dwordx2 v[132:133], v[130:131], off
	ds_read_b128 v[130:133], v252 offset:96
	v_or_b32_e32 v162, 24, v156
	v_or_b32_e32 v146, v136, v162
	s_mov_b64 s[34:35], -1
	s_and_b64 vcc, exec, s[36:37]
	v_ashrrev_i32_e32 v147, 31, v146
	s_cbranch_vccnz .LBB0_971
	s_mov_b64 s[34:35], 0
.LBB0_971:
	v_pk_mul_f32 v[148:149], v[126:127], v[180:181]
	s_andn2_b64 vcc, exec, s[34:35]
	s_waitcnt vmcnt(8) lgkmcnt(0)
	v_pk_mul_f32 v[130:131], v[148:149], v[130:131]
	v_pk_mul_f32 v[148:149], v[128:129], v[180:181]
	s_nop 0
	v_pk_mul_f32 v[132:133], v[148:149], v[132:133]
	s_cbranch_vccnz .LBB0_973
	s_ashr_i32 s34, s24, 31
	v_mov_b32_e32 v137, s34
	v_subrev_co_u32_e32 v148, vcc, s24, v1
	v_mov_b32_e32 v163, v0
	s_nop 0
	v_subb_co_u32_e32 v149, vcc, v203, v137, vcc
	v_lshl_add_u64 v[148:149], v[148:149], 0, v[162:163]
	v_lshl_add_u64 v[148:149], v[148:149], 2, v[172:173]
	global_store_dwordx4 v[148:149], v[130:133], off offset:-2048
.LBB0_973:
	s_nop 1
	v_pk_mul_f32 v[130:131], s[22:23], v[130:131]
	v_pk_mul_f32 v[132:133], s[22:23], v[132:133]
	v_cvt_pk_bf16_f32 v130, v130, v131
	v_cvt_pk_bf16_f32 v131, v132, v133
	v_lshl_add_u64 v[132:133], v[146:147], 1, v[174:175]
	global_store_dwordx2 v[132:133], v[130:131], off
	ds_read_b128 v[130:133], v252 offset:128
	v_or_b32_e32 v164, 32, v156
	v_or_b32_e32 v148, v136, v164
	s_mov_b64 s[34:35], -1
	s_and_b64 vcc, exec, s[36:37]
	v_ashrrev_i32_e32 v149, 31, v148
	s_cbranch_vccnz .LBB0_975
	s_mov_b64 s[34:35], 0
.LBB0_975:
	v_pk_mul_f32 v[150:151], v[82:83], v[180:181]
	s_andn2_b64 vcc, exec, s[34:35]
	s_waitcnt vmcnt(8) lgkmcnt(0)
	v_pk_mul_f32 v[130:131], v[150:151], v[130:131]
	v_pk_mul_f32 v[150:151], v[84:85], v[180:181]
	s_nop 0
	v_pk_mul_f32 v[132:133], v[150:151], v[132:133]
	s_cbranch_vccnz .LBB0_977
	s_ashr_i32 s34, s24, 31
	v_mov_b32_e32 v137, s34
	v_subrev_co_u32_e32 v150, vcc, s24, v1
	v_mov_b32_e32 v165, v0
	s_nop 0
	v_subb_co_u32_e32 v151, vcc, v203, v137, vcc
	v_lshl_add_u64 v[150:151], v[150:151], 0, v[164:165]
	v_lshl_add_u64 v[150:151], v[150:151], 2, v[172:173]
	global_store_dwordx4 v[150:151], v[130:133], off offset:-2048
.LBB0_977:
	s_nop 1
	v_pk_mul_f32 v[130:131], s[22:23], v[130:131]
	v_pk_mul_f32 v[132:133], s[22:23], v[132:133]
	v_cvt_pk_bf16_f32 v130, v130, v131
	v_cvt_pk_bf16_f32 v131, v132, v133
	v_lshl_add_u64 v[132:133], v[148:149], 1, v[174:175]
	global_store_dwordx2 v[132:133], v[130:131], off
	ds_read_b128 v[130:133], v252 offset:160
	v_or_b32_e32 v166, 40, v156
	v_or_b32_e32 v150, v136, v166
	s_mov_b64 s[34:35], -1
	s_and_b64 vcc, exec, s[36:37]
	v_ashrrev_i32_e32 v151, 31, v150
	s_cbranch_vccnz .LBB0_979
	s_mov_b64 s[34:35], 0
.LBB0_979:
	v_pk_mul_f32 v[152:153], v[86:87], v[180:181]
	s_andn2_b64 vcc, exec, s[34:35]
	s_waitcnt vmcnt(8) lgkmcnt(0)
	v_pk_mul_f32 v[130:131], v[152:153], v[130:131]
	v_pk_mul_f32 v[152:153], v[88:89], v[180:181]
	s_nop 0
	v_pk_mul_f32 v[132:133], v[152:153], v[132:133]
	s_cbranch_vccnz .LBB0_981
	s_ashr_i32 s34, s24, 31
	v_mov_b32_e32 v137, s34
	v_subrev_co_u32_e32 v152, vcc, s24, v1
	v_mov_b32_e32 v167, v0
	s_nop 0
	v_subb_co_u32_e32 v153, vcc, v203, v137, vcc
	v_lshl_add_u64 v[152:153], v[152:153], 0, v[166:167]
	v_lshl_add_u64 v[152:153], v[152:153], 2, v[172:173]
	global_store_dwordx4 v[152:153], v[130:133], off offset:-2048
.LBB0_981:
	s_nop 1
	v_pk_mul_f32 v[130:131], s[22:23], v[130:131]
	v_pk_mul_f32 v[132:133], s[22:23], v[132:133]
	v_cvt_pk_bf16_f32 v130, v130, v131
	v_cvt_pk_bf16_f32 v131, v132, v133
	v_lshl_add_u64 v[132:133], v[150:151], 1, v[174:175]
	global_store_dwordx2 v[132:133], v[130:131], off
	ds_read_b128 v[130:133], v252 offset:192
	v_or_b32_e32 v168, 48, v156
	v_or_b32_e32 v152, v136, v168
	s_mov_b64 s[34:35], -1
	s_and_b64 vcc, exec, s[36:37]
	v_ashrrev_i32_e32 v153, 31, v152
	s_cbranch_vccnz .LBB0_983
	s_mov_b64 s[34:35], 0
.LBB0_983:
	v_pk_mul_f32 v[154:155], v[90:91], v[180:181]
	s_andn2_b64 vcc, exec, s[34:35]
	s_waitcnt vmcnt(8) lgkmcnt(0)
	v_pk_mul_f32 v[130:131], v[154:155], v[130:131]
	v_pk_mul_f32 v[154:155], v[92:93], v[180:181]
	s_nop 0
	v_pk_mul_f32 v[132:133], v[154:155], v[132:133]
	s_cbranch_vccnz .LBB0_985
	s_ashr_i32 s34, s24, 31
	v_mov_b32_e32 v137, s34
	v_subrev_co_u32_e32 v154, vcc, s24, v1
	v_mov_b32_e32 v169, v0
	s_nop 0
	v_subb_co_u32_e32 v155, vcc, v203, v137, vcc
	v_lshl_add_u64 v[154:155], v[154:155], 0, v[168:169]
	v_lshl_add_u64 v[154:155], v[154:155], 2, v[172:173]
	global_store_dwordx4 v[154:155], v[130:133], off offset:-2048
.LBB0_985:
	s_nop 1
	v_pk_mul_f32 v[130:131], s[22:23], v[130:131]
	v_pk_mul_f32 v[132:133], s[22:23], v[132:133]
	v_cvt_pk_bf16_f32 v130, v130, v131
	v_cvt_pk_bf16_f32 v131, v132, v133
	v_lshl_add_u64 v[132:133], v[152:153], 1, v[174:175]
	global_store_dwordx2 v[132:133], v[130:131], off
	ds_read_b128 v[130:133], v252 offset:224
	v_or_b32_e32 v176, 56, v156
	v_or_b32_e32 v154, v136, v176
	s_mov_b64 s[34:35], -1
	s_and_b64 vcc, exec, s[36:37]
	v_ashrrev_i32_e32 v155, 31, v154
	s_cbranch_vccnz .LBB0_987
	s_mov_b64 s[34:35], 0
.LBB0_987:
	v_pk_mul_f32 v[204:205], v[94:95], v[180:181]
	v_pk_mul_f32 v[180:181], v[96:97], v[180:181]
	s_waitcnt vmcnt(8) lgkmcnt(0)
	v_pk_mul_f32 v[130:131], v[204:205], v[130:131]
	s_andn2_b64 vcc, exec, s[34:35]
	v_pk_mul_f32 v[132:133], v[180:181], v[132:133]
	s_cbranch_vccnz .LBB0_989
	s_ashr_i32 s34, s24, 31
	v_mov_b32_e32 v137, s34
	v_subrev_co_u32_e32 v180, vcc, s24, v1
	v_mov_b32_e32 v177, v0
	s_nop 0
	v_subb_co_u32_e32 v181, vcc, v203, v137, vcc
	v_lshl_add_u64 v[180:181], v[180:181], 0, v[176:177]
	v_lshl_add_u64 v[180:181], v[180:181], 2, v[172:173]
	global_store_dwordx4 v[180:181], v[130:133], off offset:-2048
.LBB0_989:
	v_mul_f32_e32 v137, v51, v51
	v_fmac_f32_e32 v137, v50, v50
	v_fmac_f32_e32 v137, v52, v52
	v_fmac_f32_e32 v137, v53, v53
	v_fmac_f32_e32 v137, v54, v54
	v_fmac_f32_e32 v137, v55, v55
	v_fmac_f32_e32 v137, v56, v56
	v_fmac_f32_e32 v137, v57, v57
	v_fmac_f32_e32 v137, v58, v58
	v_fmac_f32_e32 v137, v59, v59
	v_fmac_f32_e32 v137, v60, v60
	v_fmac_f32_e32 v137, v61, v61
	v_fmac_f32_e32 v137, v62, v62
	v_fmac_f32_e32 v137, v63, v63
	v_fmac_f32_e32 v137, v64, v64
	v_fmac_f32_e32 v137, v65, v65
	v_fmac_f32_e32 v137, v18, v18
	v_fmac_f32_e32 v137, v19, v19
	v_fmac_f32_e32 v137, v20, v20
	v_fmac_f32_e32 v137, v21, v21
	v_fmac_f32_e32 v137, v22, v22
	v_fmac_f32_e32 v137, v23, v23
	v_pk_mul_f32 v[206:207], v[24:25], v[24:25]
	v_pk_mul_f32 v[204:205], v[26:27], v[26:27]
	v_add_f32_e32 v137, v206, v137
	v_add_f32_e32 v137, v207, v137
	v_add_f32_e32 v137, v204, v137
	v_pk_mul_f32 v[130:131], s[22:23], v[130:131]
	v_pk_mul_f32 v[132:133], s[22:23], v[132:133]
	v_pk_mul_f32 v[180:181], v[28:29], v[28:29]
	v_add_f32_e32 v137, v205, v137
	v_cvt_pk_bf16_f32 v130, v130, v131
	v_cvt_pk_bf16_f32 v131, v132, v133
	v_lshl_add_u64 v[132:133], v[154:155], 1, v[174:175]
	v_add_f32_e32 v137, v180, v137
	global_store_dwordx2 v[132:133], v[130:131], off
	v_pk_mul_f32 v[132:133], v[30:31], v[30:31]
	v_add_f32_e32 v137, v181, v137
	v_add_f32_e32 v132, v132, v137
	v_pk_mul_f32 v[130:131], v[32:33], v[32:33]
	v_add_f32_e32 v132, v133, v132
	v_add_f32_e32 v130, v130, v132
	v_add_f32_e32 v130, v131, v130
	ds_bpermute_b32 v131, v135, v130
	v_or_b32_e32 v171, 64, v136
	s_mov_b32 s4, 0x800000
	v_or_b32_e32 v136, v171, v156
	s_mov_b64 s[34:35], -1
	s_waitcnt lgkmcnt(0)
	v_add_f32_e32 v130, v130, v131
	v_fmamk_f32 v157, v130, 0x3c800000, v188
	ds_read_b128 v[130:133], v252
	v_cmp_gt_f32_e64 s[38:39], s4, v157
	s_and_b64 vcc, exec, s[36:37]
	v_ashrrev_i32_e32 v137, 31, v136
	s_cbranch_vccnz .LBB0_991
	s_mov_b64 s[34:35], 0
.LBB0_991:
	v_mul_f32_e32 v159, 0x4b800000, v157
	v_cndmask_b32_e64 v157, v157, v159, s[38:39]
	v_rsq_f32_e32 v157, v157
	s_andn2_b64 vcc, exec, s[34:35]
	v_mul_f32_e32 v159, 0x45800000, v157
	v_cndmask_b32_e64 v180, v157, v159, s[38:39]
	v_pk_mul_f32 v[204:205], v[50:51], v[180:181] op_sel_hi:[1,0]
	s_waitcnt vmcnt(8) lgkmcnt(0)
	v_pk_mul_f32 v[130:131], v[130:131], v[204:205]
	v_pk_mul_f32 v[204:205], v[52:53], v[180:181] op_sel_hi:[1,0]
	s_nop 0
	v_pk_mul_f32 v[132:133], v[132:133], v[204:205]
	s_cbranch_vccnz .LBB0_993
	s_ashr_i32 s34, s24, 31
	v_mov_b32_e32 v159, s34
	v_subrev_co_u32_e32 v204, vcc, s24, v1
	v_mov_b32_e32 v157, v0
	s_nop 0
	v_subb_co_u32_e32 v205, vcc, v203, v159, vcc
	v_lshl_add_u64 v[156:157], v[204:205], 0, v[156:157]
	v_lshl_add_u64 v[156:157], v[156:157], 2, v[172:173]
	global_store_dwordx4 v[156:157], v[130:133], off offset:-1792
.LBB0_993:
	s_nop 1
	v_pk_mul_f32 v[130:131], s[22:23], v[130:131]
	v_pk_mul_f32 v[132:133], s[22:23], v[132:133]
	v_cvt_pk_bf16_f32 v130, v130, v131
	v_cvt_pk_bf16_f32 v131, v132, v133
	v_lshl_add_u64 v[132:133], v[136:137], 1, v[174:175]
	global_store_dwordx2 v[132:133], v[130:131], off
	ds_read_b128 v[130:133], v252 offset:32
	v_or_b32_e32 v156, v171, v158
	s_mov_b64 s[34:35], -1
	s_and_b64 vcc, exec, s[36:37]
	v_ashrrev_i32_e32 v157, 31, v156
	s_cbranch_vccnz .LBB0_995
	s_mov_b64 s[34:35], 0
.LBB0_995:
	v_mov_b32_e32 v181, v180
	v_pk_mul_f32 v[204:205], v[54:55], v[180:181]
	s_andn2_b64 vcc, exec, s[34:35]
	s_waitcnt vmcnt(8) lgkmcnt(0)
	v_pk_mul_f32 v[130:131], v[204:205], v[130:131]
	v_pk_mul_f32 v[204:205], v[56:57], v[180:181]
	s_nop 0
	v_pk_mul_f32 v[132:133], v[204:205], v[132:133]
	s_cbranch_vccnz .LBB0_997
	s_ashr_i32 s34, s24, 31
	v_mov_b32_e32 v161, s34
	v_subrev_co_u32_e32 v204, vcc, s24, v1
	v_mov_b32_e32 v159, v0
	s_nop 0
	v_subb_co_u32_e32 v205, vcc, v203, v161, vcc
	v_lshl_add_u64 v[158:159], v[204:205], 0, v[158:159]
	v_lshl_add_u64 v[158:159], v[158:159], 2, v[172:173]
	global_store_dwordx4 v[158:159], v[130:133], off offset:-1792
.LBB0_997:
	s_nop 1
	v_pk_mul_f32 v[130:131], s[22:23], v[130:131]
	v_pk_mul_f32 v[132:133], s[22:23], v[132:133]
	v_cvt_pk_bf16_f32 v130, v130, v131
	v_cvt_pk_bf16_f32 v131, v132, v133
	v_lshl_add_u64 v[132:133], v[156:157], 1, v[174:175]
	global_store_dwordx2 v[132:133], v[130:131], off
	ds_read_b128 v[130:133], v252 offset:64
	v_or_b32_e32 v158, v171, v160
	s_mov_b64 s[34:35], -1
	s_and_b64 vcc, exec, s[36:37]
	v_ashrrev_i32_e32 v159, 31, v158
	s_cbranch_vccnz .LBB0_999
	s_mov_b64 s[34:35], 0
.LBB0_999:
	v_pk_mul_f32 v[204:205], v[58:59], v[180:181]
	s_andn2_b64 vcc, exec, s[34:35]
	s_waitcnt vmcnt(8) lgkmcnt(0)
	v_pk_mul_f32 v[130:131], v[204:205], v[130:131]
	v_pk_mul_f32 v[204:205], v[60:61], v[180:181]
	s_nop 0
	v_pk_mul_f32 v[132:133], v[204:205], v[132:133]
	s_cbranch_vccnz .LBB0_1001
	s_ashr_i32 s34, s24, 31
	v_mov_b32_e32 v163, s34
	v_subrev_co_u32_e32 v204, vcc, s24, v1
	v_mov_b32_e32 v161, v0
	s_nop 0
	v_subb_co_u32_e32 v205, vcc, v203, v163, vcc
	v_lshl_add_u64 v[160:161], v[204:205], 0, v[160:161]
	v_lshl_add_u64 v[160:161], v[160:161], 2, v[172:173]
	global_store_dwordx4 v[160:161], v[130:133], off offset:-1792
.LBB0_1001:
	s_nop 1
	v_pk_mul_f32 v[130:131], s[22:23], v[130:131]
	v_pk_mul_f32 v[132:133], s[22:23], v[132:133]
	v_cvt_pk_bf16_f32 v130, v130, v131
	v_cvt_pk_bf16_f32 v131, v132, v133
	v_lshl_add_u64 v[132:133], v[158:159], 1, v[174:175]
	global_store_dwordx2 v[132:133], v[130:131], off
	ds_read_b128 v[130:133], v252 offset:96
	v_or_b32_e32 v160, v171, v162
	s_mov_b64 s[34:35], -1
	s_and_b64 vcc, exec, s[36:37]
	v_ashrrev_i32_e32 v161, 31, v160
	s_cbranch_vccnz .LBB0_1003
	s_mov_b64 s[34:35], 0
.LBB0_1003:
	v_pk_mul_f32 v[204:205], v[62:63], v[180:181]
	s_andn2_b64 vcc, exec, s[34:35]
	s_waitcnt vmcnt(8) lgkmcnt(0)
	v_pk_mul_f32 v[130:131], v[204:205], v[130:131]
	v_pk_mul_f32 v[204:205], v[64:65], v[180:181]
	s_nop 0
	v_pk_mul_f32 v[132:133], v[204:205], v[132:133]
	s_cbranch_vccnz .LBB0_1005
	s_ashr_i32 s34, s24, 31
	v_mov_b32_e32 v165, s34
	v_subrev_co_u32_e32 v204, vcc, s24, v1
	v_mov_b32_e32 v163, v0
	s_nop 0
	v_subb_co_u32_e32 v205, vcc, v203, v165, vcc
	v_lshl_add_u64 v[162:163], v[204:205], 0, v[162:163]
	v_lshl_add_u64 v[162:163], v[162:163], 2, v[172:173]
	global_store_dwordx4 v[162:163], v[130:133], off offset:-1792
.LBB0_1005:
	s_nop 1
	v_pk_mul_f32 v[130:131], s[22:23], v[130:131]
	v_pk_mul_f32 v[132:133], s[22:23], v[132:133]
	v_cvt_pk_bf16_f32 v130, v130, v131
	v_cvt_pk_bf16_f32 v131, v132, v133
	v_lshl_add_u64 v[132:133], v[160:161], 1, v[174:175]
	global_store_dwordx2 v[132:133], v[130:131], off
	ds_read_b128 v[130:133], v252 offset:128
	v_or_b32_e32 v162, v171, v164
	s_mov_b64 s[34:35], -1
	s_and_b64 vcc, exec, s[36:37]
	v_ashrrev_i32_e32 v163, 31, v162
	s_cbranch_vccnz .LBB0_1007
	s_mov_b64 s[34:35], 0
.LBB0_1007:
	v_pk_mul_f32 v[204:205], v[18:19], v[180:181]
	s_andn2_b64 vcc, exec, s[34:35]
	s_waitcnt vmcnt(8) lgkmcnt(0)
	v_pk_mul_f32 v[130:131], v[204:205], v[130:131]
	v_pk_mul_f32 v[204:205], v[20:21], v[180:181]
	s_nop 0
	v_pk_mul_f32 v[132:133], v[204:205], v[132:133]
	s_cbranch_vccnz .LBB0_1009
	s_ashr_i32 s34, s24, 31
	v_mov_b32_e32 v167, s34
	v_subrev_co_u32_e32 v204, vcc, s24, v1
	v_mov_b32_e32 v165, v0
	s_nop 0
	v_subb_co_u32_e32 v205, vcc, v203, v167, vcc
	v_lshl_add_u64 v[164:165], v[204:205], 0, v[164:165]
	v_lshl_add_u64 v[164:165], v[164:165], 2, v[172:173]
	global_store_dwordx4 v[164:165], v[130:133], off offset:-1792
.LBB0_1009:
	s_nop 1
	v_pk_mul_f32 v[130:131], s[22:23], v[130:131]
	v_pk_mul_f32 v[132:133], s[22:23], v[132:133]
	v_cvt_pk_bf16_f32 v130, v130, v131
	v_cvt_pk_bf16_f32 v131, v132, v133
	v_lshl_add_u64 v[132:133], v[162:163], 1, v[174:175]
	global_store_dwordx2 v[132:133], v[130:131], off
	ds_read_b128 v[130:133], v252 offset:160
	v_or_b32_e32 v164, v171, v166
	s_mov_b64 s[34:35], -1
	s_and_b64 vcc, exec, s[36:37]
	v_ashrrev_i32_e32 v165, 31, v164
	s_cbranch_vccnz .LBB0_1011
	s_mov_b64 s[34:35], 0
.LBB0_1011:
	v_pk_mul_f32 v[204:205], v[22:23], v[180:181]
	s_andn2_b64 vcc, exec, s[34:35]
	s_waitcnt vmcnt(8) lgkmcnt(0)
	v_pk_mul_f32 v[130:131], v[204:205], v[130:131]
	v_pk_mul_f32 v[204:205], v[24:25], v[180:181]
	s_nop 0
	v_pk_mul_f32 v[132:133], v[204:205], v[132:133]
	s_cbranch_vccnz .LBB0_1013
	s_ashr_i32 s34, s24, 31
	v_mov_b32_e32 v169, s34
	v_subrev_co_u32_e32 v204, vcc, s24, v1
	v_mov_b32_e32 v167, v0
	s_nop 0
	v_subb_co_u32_e32 v205, vcc, v203, v169, vcc
	v_lshl_add_u64 v[166:167], v[204:205], 0, v[166:167]
	v_lshl_add_u64 v[166:167], v[166:167], 2, v[172:173]
	global_store_dwordx4 v[166:167], v[130:133], off offset:-1792
.LBB0_1013:
	s_nop 1
	v_pk_mul_f32 v[130:131], s[22:23], v[130:131]
	v_pk_mul_f32 v[132:133], s[22:23], v[132:133]
	v_cvt_pk_bf16_f32 v130, v130, v131
	v_cvt_pk_bf16_f32 v131, v132, v133
	v_lshl_add_u64 v[132:133], v[164:165], 1, v[174:175]
	global_store_dwordx2 v[132:133], v[130:131], off
	ds_read_b128 v[130:133], v252 offset:192
	v_or_b32_e32 v166, v171, v168
	s_mov_b64 s[34:35], -1
	s_and_b64 vcc, exec, s[36:37]
	v_ashrrev_i32_e32 v167, 31, v166
	s_cbranch_vccnz .LBB0_1015
	s_mov_b64 s[34:35], 0
.LBB0_1015:
	v_pk_mul_f32 v[204:205], v[26:27], v[180:181]
	s_andn2_b64 vcc, exec, s[34:35]
	s_waitcnt vmcnt(8) lgkmcnt(0)
	v_pk_mul_f32 v[130:131], v[204:205], v[130:131]
	v_pk_mul_f32 v[204:205], v[28:29], v[180:181]
	s_nop 0
	v_pk_mul_f32 v[132:133], v[204:205], v[132:133]
	s_cbranch_vccnz .LBB0_1017
	s_ashr_i32 s34, s24, 31
	v_mov_b32_e32 v177, s34
	v_subrev_co_u32_e32 v204, vcc, s24, v1
	v_mov_b32_e32 v169, v0
	s_nop 0
	v_subb_co_u32_e32 v205, vcc, v203, v177, vcc
	v_lshl_add_u64 v[168:169], v[204:205], 0, v[168:169]
	v_lshl_add_u64 v[168:169], v[168:169], 2, v[172:173]
	global_store_dwordx4 v[168:169], v[130:133], off offset:-1792
.LBB0_1017:
	s_nop 1
	v_pk_mul_f32 v[130:131], s[22:23], v[130:131]
	v_pk_mul_f32 v[132:133], s[22:23], v[132:133]
	v_cvt_pk_bf16_f32 v130, v130, v131
	v_cvt_pk_bf16_f32 v131, v132, v133
	v_lshl_add_u64 v[132:133], v[166:167], 1, v[174:175]
	global_store_dwordx2 v[132:133], v[130:131], off
	ds_read_b128 v[130:133], v252 offset:224
	v_or_b32_e32 v168, v171, v176
	s_mov_b64 s[34:35], -1
	s_and_b64 vcc, exec, s[36:37]
	v_ashrrev_i32_e32 v169, 31, v168
	s_cbranch_vccnz .LBB0_1019
	s_mov_b64 s[34:35], 0
.LBB0_1019:
	v_pk_mul_f32 v[204:205], v[30:31], v[180:181]
	v_pk_mul_f32 v[180:181], v[32:33], v[180:181]
	s_waitcnt vmcnt(8) lgkmcnt(0)
	v_pk_mul_f32 v[130:131], v[204:205], v[130:131]
	s_andn2_b64 vcc, exec, s[34:35]
	v_pk_mul_f32 v[132:133], v[180:181], v[132:133]
	s_cbranch_vccnz .LBB0_1021
	s_ashr_i32 s34, s24, 31
	v_mov_b32_e32 v171, s34
	v_subrev_co_u32_e32 v180, vcc, s24, v1
	v_mov_b32_e32 v177, v0
	s_nop 0
	v_subb_co_u32_e32 v181, vcc, v203, v171, vcc
	v_lshl_add_u64 v[176:177], v[180:181], 0, v[176:177]
	v_lshl_add_u64 v[172:173], v[176:177], 2, v[172:173]
	global_store_dwordx4 v[172:173], v[130:133], off offset:-1792
.LBB0_1021:
	v_mul_f32_e32 v203, v99, v99
	v_fmac_f32_e32 v203, v98, v98
	v_fmac_f32_e32 v203, v100, v100
	v_fmac_f32_e32 v203, v101, v101
	v_fmac_f32_e32 v203, v102, v102
	v_fmac_f32_e32 v203, v103, v103
	v_fmac_f32_e32 v203, v104, v104
	v_fmac_f32_e32 v203, v105, v105
	v_fmac_f32_e32 v203, v106, v106
	v_fmac_f32_e32 v203, v107, v107
	v_fmac_f32_e32 v203, v108, v108
	v_fmac_f32_e32 v203, v109, v109
	v_fmac_f32_e32 v203, v110, v110
	v_fmac_f32_e32 v203, v111, v111
	v_fmac_f32_e32 v203, v112, v112
	v_fmac_f32_e32 v203, v113, v113
	v_fmac_f32_e32 v203, v66, v66
	v_fmac_f32_e32 v203, v67, v67
	v_fmac_f32_e32 v203, v68, v68
	v_fmac_f32_e32 v203, v69, v69
	v_fmac_f32_e32 v203, v70, v70
	v_fmac_f32_e32 v203, v71, v71
	v_pk_mul_f32 v[180:181], v[72:73], v[72:73]
	v_pk_mul_f32 v[176:177], v[74:75], v[74:75]
	v_add_f32_e32 v180, v180, v203
	v_add_f32_e32 v180, v181, v180
	v_pk_mul_f32 v[130:131], s[22:23], v[130:131]
	v_pk_mul_f32 v[132:133], s[22:23], v[132:133]
	v_add_f32_e32 v176, v176, v180
	v_cvt_pk_bf16_f32 v130, v130, v131
	v_cvt_pk_bf16_f32 v131, v132, v133
	v_lshl_add_u64 v[132:133], v[168:169], 1, v[174:175]
	v_pk_mul_f32 v[174:175], v[76:77], v[76:77]
	v_add_f32_e32 v176, v177, v176
	v_add_f32_e32 v174, v174, v176
	global_store_dwordx2 v[132:133], v[130:131], off
	v_pk_mul_f32 v[132:133], v[78:79], v[78:79]
	v_add_f32_e32 v174, v175, v174
	v_add_f32_e32 v132, v132, v174
	v_pk_mul_f32 v[130:131], v[80:81], v[80:81]
	v_add_f32_e32 v132, v133, v132
	v_add_f32_e32 v130, v130, v132
	v_add_f32_e32 v130, v131, v130
	ds_bpermute_b32 v131, v135, v130
	v_or_b32_e32 v172, 32, v170
	v_ashrrev_i32_e32 v173, 31, v172
	v_lshlrev_b64 v[170:171], 11, v[172:173]
	s_waitcnt lgkmcnt(0)
	v_add_f32_e32 v130, v130, v131
	v_fmamk_f32 v130, v130, 0x3c800000, v188
	v_cmp_gt_f32_e32 vcc, s4, v130
	v_mul_f32_e32 v131, 0x4b800000, v130
	s_nop 0
	v_cndmask_b32_e32 v130, v130, v131, vcc
	v_rsq_f32_e32 v130, v130
	s_nop 0
	v_mul_f32_e32 v131, 0x45800000, v130
	v_cndmask_b32_e32 v174, v130, v131, vcc
	ds_read_b128 v[130:133], v252
	v_pk_mul_f32 v[176:177], v[98:99], v[174:175] op_sel_hi:[1,0]
	s_andn2_b64 vcc, exec, s[0:1]
	s_waitcnt vmcnt(8) lgkmcnt(0)
	v_pk_mul_f32 v[130:131], v[130:131], v[176:177]
	v_pk_mul_f32 v[176:177], v[100:101], v[174:175] op_sel_hi:[1,0]
	v_cndmask_b32_e64 v175, 0, 1, s[0:1]
	v_readlane_b32 s0, v246, 44
	v_readlane_b32 s1, v246, 45
	v_pk_mul_f32 v[132:133], v[132:133], v[176:177]
	v_cmp_ne_u32_e64 s[36:37], 1, v175
	v_lshl_add_u64 v[170:171], s[0:1], 0, v[170:171]
	s_cbranch_vccnz .LBB0_1023
	v_lshl_add_u64 v[176:177], v[140:141], 2, v[170:171]
	global_store_dwordx4 v[176:177], v[130:133], off
.LBB0_1023:
	v_lshlrev_b64 v[172:173], 10, v[172:173]
	v_lshl_add_u64 v[172:173], s[28:29], 0, v[172:173]
	v_pk_mul_f32 v[130:131], s[22:23], v[130:131]
	v_pk_mul_f32 v[132:133], s[22:23], v[132:133]
	v_cvt_pk_bf16_f32 v130, v130, v131
	v_cvt_pk_bf16_f32 v131, v132, v133
	v_lshl_add_u64 v[132:133], v[140:141], 1, v[172:173]
	global_store_dwordx2 v[132:133], v[130:131], off
	ds_read_b128 v[130:133], v252 offset:32
	v_mov_b32_e32 v175, v174
	v_pk_mul_f32 v[140:141], v[102:103], v[174:175]
	s_and_b64 vcc, exec, s[36:37]
	s_waitcnt vmcnt(8) lgkmcnt(0)
	v_pk_mul_f32 v[130:131], v[140:141], v[130:131]
	v_pk_mul_f32 v[140:141], v[104:105], v[174:175]
	s_nop 0
	v_pk_mul_f32 v[132:133], v[140:141], v[132:133]
	s_cbranch_vccnz .LBB0_1025
	v_lshl_add_u64 v[140:141], v[142:143], 2, v[170:171]
	global_store_dwordx4 v[140:141], v[130:133], off
.LBB0_1025:
	s_nop 1
	v_pk_mul_f32 v[130:131], s[22:23], v[130:131]
	v_pk_mul_f32 v[132:133], s[22:23], v[132:133]
	v_cvt_pk_bf16_f32 v130, v130, v131
	v_cvt_pk_bf16_f32 v131, v132, v133
	v_lshl_add_u64 v[132:133], v[142:143], 1, v[172:173]
	global_store_dwordx2 v[132:133], v[130:131], off
	ds_read_b128 v[130:133], v252 offset:64
	v_pk_mul_f32 v[140:141], v[106:107], v[174:175]
	s_and_b64 vcc, exec, s[36:37]
	s_mov_b32 s0, 0x800000
	s_waitcnt vmcnt(8) lgkmcnt(0)
	v_pk_mul_f32 v[130:131], v[140:141], v[130:131]
	v_pk_mul_f32 v[140:141], v[108:109], v[174:175]
	s_nop 0
	v_pk_mul_f32 v[132:133], v[140:141], v[132:133]
	s_cbranch_vccnz .LBB0_1027
	v_lshl_add_u64 v[140:141], v[144:145], 2, v[170:171]
	global_store_dwordx4 v[140:141], v[130:133], off
.LBB0_1027:
	s_nop 1
	v_pk_mul_f32 v[130:131], s[22:23], v[130:131]
	v_pk_mul_f32 v[132:133], s[22:23], v[132:133]
	v_cvt_pk_bf16_f32 v130, v130, v131
	v_cvt_pk_bf16_f32 v131, v132, v133
	v_lshl_add_u64 v[132:133], v[144:145], 1, v[172:173]
	global_store_dwordx2 v[132:133], v[130:131], off
	ds_read_b128 v[130:133], v252 offset:96
	v_pk_mul_f32 v[140:141], v[110:111], v[174:175]
	s_and_b64 vcc, exec, s[36:37]
	s_waitcnt vmcnt(8) lgkmcnt(0)
	v_pk_mul_f32 v[130:131], v[140:141], v[130:131]
	v_pk_mul_f32 v[140:141], v[112:113], v[174:175]
	s_nop 0
	v_pk_mul_f32 v[132:133], v[140:141], v[132:133]
	s_cbranch_vccnz .LBB0_1029
	v_lshl_add_u64 v[140:141], v[146:147], 2, v[170:171]
	global_store_dwordx4 v[140:141], v[130:133], off
.LBB0_1029:
	s_nop 1
	v_pk_mul_f32 v[130:131], s[22:23], v[130:131]
	v_pk_mul_f32 v[132:133], s[22:23], v[132:133]
	v_cvt_pk_bf16_f32 v130, v130, v131
	v_cvt_pk_bf16_f32 v131, v132, v133
	v_lshl_add_u64 v[132:133], v[146:147], 1, v[172:173]
	global_store_dwordx2 v[132:133], v[130:131], off
	ds_read_b128 v[130:133], v252 offset:128
	v_pk_mul_f32 v[140:141], v[66:67], v[174:175]
	s_and_b64 vcc, exec, s[36:37]
	s_waitcnt vmcnt(8) lgkmcnt(0)
	v_pk_mul_f32 v[130:131], v[140:141], v[130:131]
	v_pk_mul_f32 v[140:141], v[68:69], v[174:175]
	s_nop 0
	v_pk_mul_f32 v[132:133], v[140:141], v[132:133]
	s_cbranch_vccnz .LBB0_1031
	v_lshl_add_u64 v[140:141], v[148:149], 2, v[170:171]
	global_store_dwordx4 v[140:141], v[130:133], off
.LBB0_1031:
	s_nop 1
	v_pk_mul_f32 v[130:131], s[22:23], v[130:131]
	v_pk_mul_f32 v[132:133], s[22:23], v[132:133]
	v_cvt_pk_bf16_f32 v130, v130, v131
	v_cvt_pk_bf16_f32 v131, v132, v133
	v_lshl_add_u64 v[132:133], v[148:149], 1, v[172:173]
	global_store_dwordx2 v[132:133], v[130:131], off
	ds_read_b128 v[130:133], v252 offset:160
	v_pk_mul_f32 v[140:141], v[70:71], v[174:175]
	s_and_b64 vcc, exec, s[36:37]
	s_waitcnt vmcnt(8) lgkmcnt(0)
	v_pk_mul_f32 v[130:131], v[140:141], v[130:131]
	v_pk_mul_f32 v[140:141], v[72:73], v[174:175]
	s_nop 0
	v_pk_mul_f32 v[132:133], v[140:141], v[132:133]
	s_cbranch_vccnz .LBB0_1033
	v_lshl_add_u64 v[140:141], v[150:151], 2, v[170:171]
	global_store_dwordx4 v[140:141], v[130:133], off
.LBB0_1033:
	s_nop 1
	v_pk_mul_f32 v[130:131], s[22:23], v[130:131]
	v_pk_mul_f32 v[132:133], s[22:23], v[132:133]
	v_cvt_pk_bf16_f32 v130, v130, v131
	v_cvt_pk_bf16_f32 v131, v132, v133
	v_lshl_add_u64 v[132:133], v[150:151], 1, v[172:173]
	global_store_dwordx2 v[132:133], v[130:131], off
	ds_read_b128 v[130:133], v252 offset:192
	v_pk_mul_f32 v[140:141], v[74:75], v[174:175]
	s_and_b64 vcc, exec, s[36:37]
	s_waitcnt vmcnt(8) lgkmcnt(0)
	v_pk_mul_f32 v[130:131], v[140:141], v[130:131]
	v_pk_mul_f32 v[140:141], v[76:77], v[174:175]
	s_nop 0
	v_pk_mul_f32 v[132:133], v[140:141], v[132:133]
	s_cbranch_vccnz .LBB0_1035
	v_lshl_add_u64 v[140:141], v[152:153], 2, v[170:171]
	global_store_dwordx4 v[140:141], v[130:133], off
.LBB0_1035:
	s_nop 1
	v_pk_mul_f32 v[130:131], s[22:23], v[130:131]
	v_pk_mul_f32 v[132:133], s[22:23], v[132:133]
	v_cvt_pk_bf16_f32 v130, v130, v131
	v_cvt_pk_bf16_f32 v131, v132, v133
	v_lshl_add_u64 v[132:133], v[152:153], 1, v[172:173]
	global_store_dwordx2 v[132:133], v[130:131], off
	ds_read_b128 v[130:133], v252 offset:224
	v_pk_mul_f32 v[140:141], v[78:79], v[174:175]
	v_pk_mul_f32 v[142:143], v[80:81], v[174:175]
	s_and_b64 vcc, exec, s[36:37]
	s_waitcnt vmcnt(8) lgkmcnt(0)
	v_pk_mul_f32 v[130:131], v[140:141], v[130:131]
	v_pk_mul_f32 v[132:133], v[142:143], v[132:133]
	s_cbranch_vccnz .LBB0_1037
	v_lshl_add_u64 v[140:141], v[154:155], 2, v[170:171]
	global_store_dwordx4 v[140:141], v[130:133], off
.LBB0_1037:
	v_mul_f32_e32 v146, v35, v35
	v_fmac_f32_e32 v146, v34, v34
	v_fmac_f32_e32 v146, v36, v36
	v_fmac_f32_e32 v146, v37, v37
	v_fmac_f32_e32 v146, v38, v38
	v_fmac_f32_e32 v146, v39, v39
	v_fmac_f32_e32 v146, v40, v40
	v_fmac_f32_e32 v146, v41, v41
	v_fmac_f32_e32 v146, v42, v42
	v_fmac_f32_e32 v146, v43, v43
	v_fmac_f32_e32 v146, v44, v44
	v_fmac_f32_e32 v146, v45, v45
	v_fmac_f32_e32 v146, v46, v46
	v_fmac_f32_e32 v146, v47, v47
	v_fmac_f32_e32 v146, v48, v48
	v_fmac_f32_e32 v146, v49, v49
	v_fmac_f32_e32 v146, v2, v2
	v_fmac_f32_e32 v146, v3, v3
	v_fmac_f32_e32 v146, v4, v4
	v_fmac_f32_e32 v146, v5, v5
	v_fmac_f32_e32 v146, v6, v6
	v_fmac_f32_e32 v146, v7, v7
	v_pk_mul_f32 v[144:145], v[8:9], v[8:9]
	v_pk_mul_f32 v[142:143], v[10:11], v[10:11]
	v_add_f32_e32 v144, v144, v146
	v_add_f32_e32 v144, v145, v144
	v_add_f32_e32 v142, v142, v144
	v_pk_mul_f32 v[130:131], s[22:23], v[130:131]
	v_pk_mul_f32 v[132:133], s[22:23], v[132:133]
	v_pk_mul_f32 v[140:141], v[12:13], v[12:13]
	v_add_f32_e32 v142, v143, v142
	v_cvt_pk_bf16_f32 v130, v130, v131
	v_cvt_pk_bf16_f32 v131, v132, v133
	v_lshl_add_u64 v[132:133], v[154:155], 1, v[172:173]
	v_add_f32_e32 v140, v140, v142
	global_store_dwordx2 v[132:133], v[130:131], off
	v_pk_mul_f32 v[132:133], v[14:15], v[14:15]
	v_add_f32_e32 v140, v141, v140
	v_add_f32_e32 v132, v132, v140
	v_pk_mul_f32 v[130:131], v[16:17], v[16:17]
	v_add_f32_e32 v132, v133, v132
	v_add_f32_e32 v130, v130, v132
	v_add_f32_e32 v130, v131, v130
	ds_bpermute_b32 v131, v135, v130
	s_waitcnt lgkmcnt(0)
	v_add_f32_e32 v130, v130, v131
	v_fmamk_f32 v130, v130, 0x3c800000, v188
	v_cmp_gt_f32_e32 vcc, s0, v130
	v_mul_f32_e32 v131, 0x4b800000, v130
	s_nop 0
	v_cndmask_b32_e32 v130, v130, v131, vcc
	v_rsq_f32_e32 v130, v130
	s_nop 0
	v_mul_f32_e32 v131, 0x45800000, v130
	v_cndmask_b32_e32 v140, v130, v131, vcc
	ds_read_b128 v[130:133], v252
	v_pk_mul_f32 v[142:143], v[34:35], v[140:141] op_sel_hi:[1,0]
	s_and_b64 vcc, exec, s[36:37]
	s_waitcnt vmcnt(8) lgkmcnt(0)
	v_pk_mul_f32 v[130:131], v[130:131], v[142:143]
	v_pk_mul_f32 v[142:143], v[36:37], v[140:141] op_sel_hi:[1,0]
	s_nop 0
	v_pk_mul_f32 v[132:133], v[132:133], v[142:143]
	s_cbranch_vccnz .LBB0_1039
	v_lshl_add_u64 v[142:143], v[136:137], 2, v[170:171]
	global_store_dwordx4 v[142:143], v[130:133], off
.LBB0_1039:
	s_nop 1
	v_pk_mul_f32 v[130:131], s[22:23], v[130:131]
	v_pk_mul_f32 v[132:133], s[22:23], v[132:133]
	v_cvt_pk_bf16_f32 v130, v130, v131
	v_cvt_pk_bf16_f32 v131, v132, v133
	v_lshl_add_u64 v[132:133], v[136:137], 1, v[172:173]
	global_store_dwordx2 v[132:133], v[130:131], off
	ds_read_b128 v[130:133], v252 offset:32
	v_mov_b32_e32 v141, v140
	v_pk_mul_f32 v[136:137], v[38:39], v[140:141]
	s_and_b64 vcc, exec, s[36:37]
	s_waitcnt vmcnt(8) lgkmcnt(0)
	v_pk_mul_f32 v[130:131], v[136:137], v[130:131]
	v_pk_mul_f32 v[136:137], v[40:41], v[140:141]
	s_nop 0
	v_pk_mul_f32 v[132:133], v[136:137], v[132:133]
	s_cbranch_vccnz .LBB0_1041
	v_lshl_add_u64 v[136:137], v[156:157], 2, v[170:171]
	global_store_dwordx4 v[136:137], v[130:133], off
.LBB0_1041:
	s_nop 1
	v_pk_mul_f32 v[130:131], s[22:23], v[130:131]
	v_pk_mul_f32 v[132:133], s[22:23], v[132:133]
	v_cvt_pk_bf16_f32 v130, v130, v131
	v_cvt_pk_bf16_f32 v131, v132, v133
	v_lshl_add_u64 v[132:133], v[156:157], 1, v[172:173]
	global_store_dwordx2 v[132:133], v[130:131], off
	ds_read_b128 v[130:133], v252 offset:64
	v_pk_mul_f32 v[136:137], v[42:43], v[140:141]
	s_and_b64 vcc, exec, s[36:37]
	s_waitcnt vmcnt(8) lgkmcnt(0)
	v_pk_mul_f32 v[130:131], v[136:137], v[130:131]
	v_pk_mul_f32 v[136:137], v[44:45], v[140:141]
	s_nop 0
	v_pk_mul_f32 v[132:133], v[136:137], v[132:133]
	s_cbranch_vccnz .LBB0_1043
	v_lshl_add_u64 v[136:137], v[158:159], 2, v[170:171]
	global_store_dwordx4 v[136:137], v[130:133], off
.LBB0_1043:
	s_nop 1
	v_pk_mul_f32 v[130:131], s[22:23], v[130:131]
	v_pk_mul_f32 v[132:133], s[22:23], v[132:133]
	v_cvt_pk_bf16_f32 v130, v130, v131
	v_cvt_pk_bf16_f32 v131, v132, v133
	v_lshl_add_u64 v[132:133], v[158:159], 1, v[172:173]
	global_store_dwordx2 v[132:133], v[130:131], off
	ds_read_b128 v[130:133], v252 offset:96
	v_pk_mul_f32 v[136:137], v[46:47], v[140:141]
	s_and_b64 vcc, exec, s[36:37]
	s_waitcnt vmcnt(8) lgkmcnt(0)
	v_pk_mul_f32 v[130:131], v[136:137], v[130:131]
	v_pk_mul_f32 v[136:137], v[48:49], v[140:141]
	s_nop 0
	v_pk_mul_f32 v[132:133], v[136:137], v[132:133]
	s_cbranch_vccnz .LBB0_1045
	v_lshl_add_u64 v[136:137], v[160:161], 2, v[170:171]
	global_store_dwordx4 v[136:137], v[130:133], off
.LBB0_1045:
	s_nop 1
	v_pk_mul_f32 v[130:131], s[22:23], v[130:131]
	v_pk_mul_f32 v[132:133], s[22:23], v[132:133]
	v_cvt_pk_bf16_f32 v130, v130, v131
	v_cvt_pk_bf16_f32 v131, v132, v133
	v_lshl_add_u64 v[132:133], v[160:161], 1, v[172:173]
	global_store_dwordx2 v[132:133], v[130:131], off
	ds_read_b128 v[130:133], v252 offset:128
	v_pk_mul_f32 v[136:137], v[2:3], v[140:141]
	s_and_b64 vcc, exec, s[36:37]
	s_waitcnt vmcnt(8) lgkmcnt(0)
	v_pk_mul_f32 v[130:131], v[136:137], v[130:131]
	v_pk_mul_f32 v[136:137], v[4:5], v[140:141]
	s_nop 0
	v_pk_mul_f32 v[132:133], v[136:137], v[132:133]
	s_cbranch_vccnz .LBB0_1047
	v_lshl_add_u64 v[136:137], v[162:163], 2, v[170:171]
	global_store_dwordx4 v[136:137], v[130:133], off
.LBB0_1047:
	s_nop 1
	v_pk_mul_f32 v[130:131], s[22:23], v[130:131]
	v_pk_mul_f32 v[132:133], s[22:23], v[132:133]
	v_cvt_pk_bf16_f32 v130, v130, v131
	v_cvt_pk_bf16_f32 v131, v132, v133
	v_lshl_add_u64 v[132:133], v[162:163], 1, v[172:173]
	global_store_dwordx2 v[132:133], v[130:131], off
	ds_read_b128 v[130:133], v252 offset:160
	v_pk_mul_f32 v[136:137], v[6:7], v[140:141]
	s_and_b64 vcc, exec, s[36:37]
	s_waitcnt vmcnt(8) lgkmcnt(0)
	v_pk_mul_f32 v[130:131], v[136:137], v[130:131]
	v_pk_mul_f32 v[136:137], v[8:9], v[140:141]
	s_nop 0
	v_pk_mul_f32 v[132:133], v[136:137], v[132:133]
	s_cbranch_vccnz .LBB0_1049
	v_lshl_add_u64 v[136:137], v[164:165], 2, v[170:171]
	global_store_dwordx4 v[136:137], v[130:133], off
.LBB0_1049:
	s_nop 1
	v_pk_mul_f32 v[130:131], s[22:23], v[130:131]
	v_pk_mul_f32 v[132:133], s[22:23], v[132:133]
	v_cvt_pk_bf16_f32 v130, v130, v131
	v_cvt_pk_bf16_f32 v131, v132, v133
	v_lshl_add_u64 v[132:133], v[164:165], 1, v[172:173]
	global_store_dwordx2 v[132:133], v[130:131], off
	ds_read_b128 v[130:133], v252 offset:192
	v_pk_mul_f32 v[136:137], v[10:11], v[140:141]
	s_and_b64 vcc, exec, s[36:37]
	s_waitcnt vmcnt(8) lgkmcnt(0)
	v_pk_mul_f32 v[130:131], v[136:137], v[130:131]
	v_pk_mul_f32 v[136:137], v[12:13], v[140:141]
	s_nop 0
	v_pk_mul_f32 v[132:133], v[136:137], v[132:133]
	s_cbranch_vccnz .LBB0_1051
	v_lshl_add_u64 v[136:137], v[166:167], 2, v[170:171]
	global_store_dwordx4 v[136:137], v[130:133], off
.LBB0_1051:
	s_nop 1
	v_pk_mul_f32 v[130:131], s[22:23], v[130:131]
	v_pk_mul_f32 v[132:133], s[22:23], v[132:133]
	v_cvt_pk_bf16_f32 v130, v130, v131
	v_cvt_pk_bf16_f32 v131, v132, v133
	v_lshl_add_u64 v[132:133], v[166:167], 1, v[172:173]
	global_store_dwordx2 v[132:133], v[130:131], off
	ds_read_b128 v[130:133], v252 offset:224
	v_pk_mul_f32 v[136:137], v[14:15], v[140:141]
	v_pk_mul_f32 v[138:139], v[16:17], v[140:141]
	s_and_b64 vcc, exec, s[36:37]
	s_waitcnt vmcnt(8) lgkmcnt(0)
	v_pk_mul_f32 v[130:131], v[136:137], v[130:131]
	v_pk_mul_f32 v[132:133], v[138:139], v[132:133]
	s_cbranch_vccnz .LBB0_1053
	v_lshl_add_u64 v[136:137], v[168:169], 2, v[170:171]
	global_store_dwordx4 v[136:137], v[130:133], off
